# NA bias: batched LDS reads + v_cndmask instead of per-element exec-masked blocks
# baseline (speedup 1.0000x reference)
.LBB0_752:
	v_mov_b32_e32 v243, 0xf149f2ca
	s_andn2_b64 vcc, exec, s[38:39]
	v_mov_b32_e32 v244, 0xf149f2ca
	v_mov_b32_e32 v107, 0xf149f2ca
	v_mov_b32_e32 v204, 0xf149f2ca
	v_mov_b32_e32 v104, 0xf149f2ca
	s_cbranch_vccnz .LBB0_762
	v_mov_b32_e32 v204, 0xf149f2ca
	v_mov_b32_e32 v107, 0xf149f2ca
	v_mov_b32_e32 v244, 0xf149f2ca
	v_mov_b32_e32 v243, 0xf149f2ca
	v_add_u32_e32 v245, s0, v207
	v_add_u32_e32 v246, s0, v208
	v_add_u32_e32 v247, s0, v209
	v_add_u32_e32 v248, s0, v210
	ds_read_b32 v245, v245 offset:9316
	ds_read_b32 v246, v246 offset:9316
	ds_read_b32 v247, v247 offset:9316
	ds_read_b32 v248, v248 offset:9316
	s_waitcnt lgkmcnt(0)
	v_fmac_f32_e32 v245, 0x3e38aa3b, v84
	v_fmac_f32_e32 v246, 0x3e38aa3b, v85
	v_fmac_f32_e32 v247, 0x3e38aa3b, v86
	v_fmac_f32_e32 v248, 0x3e38aa3b, v87
	v_cndmask_b32_e64 v204, v204, v245, s[42:43]
	v_cndmask_b32_e64 v107, v107, v246, s[44:45]
	v_cndmask_b32_e64 v244, v244, v247, s[46:47]
	v_cndmask_b32_e64 v243, v243, v248, s[48:49]
	v_max3_f32 v84, v204, s1, v107
	v_max3_f32 v104, v84, v244, v243
.LBB0_762:
	s_and_b64 vcc, exec, s[74:75]
	s_mov_b64 s[38:39], -1
	s_cbranch_vccnz .LBB0_772
	v_mov_b32_e32 v246, 0xf149f2ca
	v_mov_b32_e32 v245, 0xf149f2ca
	v_mov_b32_e32 v248, 0xf149f2ca
	v_mov_b32_e32 v247, 0xf149f2ca
	v_add_u32_e32 v249, s0, v211
	v_add_u32_e32 v250, s0, v212
	v_add_u32_e32 v251, s0, v213
	v_add_u32_e32 v235, s0, v214
	ds_read_b32 v249, v249 offset:9316
	ds_read_b32 v250, v250 offset:9316
	ds_read_b32 v251, v251 offset:9316
	ds_read_b32 v235, v235 offset:9316
	s_waitcnt lgkmcnt(0)
	v_fmac_f32_e32 v249, 0x3e38aa3b, v80
	v_fmac_f32_e32 v250, 0x3e38aa3b, v81
	v_fmac_f32_e32 v251, 0x3e38aa3b, v82
	v_fmac_f32_e32 v235, 0x3e38aa3b, v83
	v_cndmask_b32_e64 v246, v246, v249, s[50:51]
	v_cndmask_b32_e64 v245, v245, v250, s[52:53]
	v_cndmask_b32_e64 v248, v248, v251, s[54:55]
	v_cndmask_b32_e64 v247, v247, v235, s[56:57]
	v_max3_f32 v80, v104, v246, v245
	v_max3_f32 v84, v80, v248, v247
	s_branch .LBB0_774

.LBB0_774:
	s_and_b64 vcc, exec, s[76:77]
	s_mov_b64 s[38:39], -1
	s_cbranch_vccnz .LBB0_784
	v_mov_b32_e32 v250, 0xf149f2ca
	v_mov_b32_e32 v249, 0xf149f2ca
	v_mov_b32_e32 v235, 0xf149f2ca
	v_mov_b32_e32 v251, 0xf149f2ca
	v_add_u32_e32 v237, s0, v215
	v_add_u32_e32 v236, s0, v216
	v_add_u32_e32 v233, s0, v217
	v_add_u32_e32 v225, s0, v218
	ds_read_b32 v237, v237 offset:9316
	ds_read_b32 v236, v236 offset:9316
	ds_read_b32 v233, v233 offset:9316
	ds_read_b32 v225, v225 offset:9316
	s_waitcnt lgkmcnt(0)
	v_fmac_f32_e32 v237, 0x3e38aa3b, v76
	v_fmac_f32_e32 v236, 0x3e38aa3b, v77
	v_fmac_f32_e32 v233, 0x3e38aa3b, v78
	v_fmac_f32_e32 v225, 0x3e38aa3b, v79
	v_cndmask_b32_e64 v250, v250, v237, s[58:59]
	v_cndmask_b32_e64 v249, v249, v236, s[60:61]
	v_cndmask_b32_e64 v235, v235, v233, s[62:63]
	v_cndmask_b32_e64 v251, v251, v225, s[64:65]
	v_max3_f32 v76, v84, v250, v249
	v_max3_f32 v80, v76, v235, v251
	s_branch .LBB0_786

.LBB0_786:
	s_and_b64 vcc, exec, s[78:79]
	s_mov_b64 s[38:39], -1
	s_cbranch_vccnz .LBB0_796
	v_mov_b32_e32 v237, 0xf149f2ca
	v_mov_b32_e32 v236, 0xf149f2ca
	v_mov_b32_e32 v233, 0xf149f2ca
	v_mov_b32_e32 v225, 0xf149f2ca
	v_add_u32_e32 v234, s0, v219
	v_add_u32_e32 v241, s0, v220
	v_add_u32_e32 v242, s0, v221
	v_add_u32_e32 v223, s0, v222
	ds_read_b32 v234, v234 offset:9316
	ds_read_b32 v241, v241 offset:9316
	ds_read_b32 v242, v242 offset:9316
	ds_read_b32 v223, v223 offset:9316
	s_waitcnt lgkmcnt(0)
	v_fmac_f32_e32 v234, 0x3e38aa3b, v64
	v_fmac_f32_e32 v241, 0x3e38aa3b, v65
	v_fmac_f32_e32 v242, 0x3e38aa3b, v66
	v_fmac_f32_e32 v223, 0x3e38aa3b, v67
	v_cndmask_b32_e64 v237, v237, v234, s[66:67]
	v_cndmask_b32_e64 v236, v236, v241, s[68:69]
	v_cndmask_b32_e64 v233, v233, v242, s[70:71]
	v_cndmask_b32_e64 v225, v225, v223, s[72:73]
	v_max3_f32 v64, v80, v237, v236
	v_max3_f32 v76, v64, v233, v225
	s_branch .LBB0_798
